# v54: v53 + same running-max-as-MFMA-C-operand transformation in the .LBB0_381 attention units (row group 1)
# speedup vs baseline: 1.0134x; 1.0005x over previous
; #define LAS __attribute__((address_space(3)))
; __device__ __forceinline__ int opaque_tid() { int t = threadIdx.x; asm volatile("" : "+v"(t)); return t; }
; #define AT_LOAD(t_) do { const bf16_t* kn = ksrc + (size_t)(t_) * AKT * INW; const bf16_t* vn = vsrc + (t_) * AKT; \
;         kreg0 = *(const u32x4*)kn; kreg1 = *(const u32x4*)(kn + (size_t)64 * INW); vreg0 = *(const u32x4*)vn; vreg1 = *(const u32x4*)(vn + 64); } while (0)
; template <int DK, bool IS_A>
; __device__ __forceinline__ void attn_unit(const Params& P, int l, LAS unsigned char* lds, int b, int grp, int qtok0, int nkeys) {
;     const int tid = opaque_tid(), lane = tid & 63, wave = tid >> 6, s = wave >> 2, wq = wave & 3, r32 = lane & 31, hi = lane >> 5;
;     const bf16_t* proj = (const bf16_t*)(P.ws + WS_PROJ);
;     bf16_t* mix = (bf16_t*)(P.ws + WS_H);
;     const int qcol = IS_A ? PA_Q + grp * 64 + s * 32 : PC_Q + (2 * grp + s) * 64;
;     const int kcol = IS_A ? PA_K + grp * 64 : PC_K + grp * 64;
;     const int koff = IS_A ? s * 32 : 0;
;     const bf16_t* VT = IS_A ? (const bf16_t*)(P.ws + WS_VTA) + ((size_t)(b * 4 + grp) * 64) * TT : (const bf16_t*)(P.ws + WS_VTC) + ((size_t)(b * 2 + grp) * 64) * TT;
;     const size_t qrow = (size_t)b * TT + qtok0 + wq * 64 + r32;
;     bf16x8 qa[DK / 16], qb[DK / 16];
; #pragma unroll
;     for (int i = 0; i < DK / 16; ++i) { qa[i] = *(const bf16x8*)(proj + qrow * INW + qcol + i * 16 + hi * 8); qb[i] = *(const bf16x8*)(proj + (qrow + 32) * INW + qcol + i * 16 + hi * 8); }
;     const int lrow = tid >> 3, lch = tid & 7;
;     const bf16_t* ksrc = proj + ((size_t)b * TT + lrow) * INW + kcol + lch * 8;
;     const bf16_t* vsrc = VT + (size_t)lrow * TT + lch * 8;
;     const int NT = nkeys / AKT;
;     u32x4 kreg0, kreg1, vreg0, vreg1;
;     ...
;     const int kfo = r32 * AK_PITCH + (koff + 8 * hi) * 2, vfo = AK_BYTES + r32 * AV_PITCH + 8 * hi;
;     AT_LOAD(0); AT_STORE(0);
;     __syncthreads();
;     float ma = -1e30f, mb = -1e30f, la = 0.f, lb_ = 0.f;
;     f32x16 oa0, oa1, ob0, ob1;
; #pragma unroll
;     for (int r = 0; r < 16; ++r) { oa0[r] = 0.f; oa1[r] = 0.f; ob0[r] = 0.f; ob1[r] = 0.f; }
.LBB0_381:
	s_and_b64 vcc, exec, s[10:11]
	s_cbranch_vccz .LBB0_405
	s_add_i32 s8, s37, 0xfffffc50
	s_lshr_b32 s9, s8, 2
	s_lshl_b32 s8, s37, 6
	v_mov_b32_e32 v165, v200
	s_and_b32 s8, s8, 0xc0
	s_lshl_b32 s10, s9, 8
	s_or_b32 s10, s10, s8
	v_ashrrev_i32_e32 v4, 3, v165
	s_mul_i32 s64, s10, 0x900
	s_mul_i32 s10, s9, 0x900
	s_mov_b32 s11, s65
	v_ashrrev_i32_e32 v5, 31, v4
	v_mov_b64_e32 v[0:1], s[56:57]
	s_lshl_b64 s[12:13], s[64:65], 1
	v_readlane_b32 s7, v255, 8
	v_lshl_add_u64 v[2:3], v[4:5], 0, s[10:11]
	s_add_u32 s12, s7, s12
	v_readlane_b32 s7, v255, 9
	v_mad_u64_u32 v[6:7], s[18:19], v2, s23, v[0:1]
	s_addc_u32 s13, s7, s13
	v_mad_i32_i24 v7, v3, s23, v7
	s_lshl_b32 s64, s8, 1
	v_lshlrev_b32_e32 v5, 4, v165
	v_lshl_add_u64 v[2:3], v[6:7], 0, s[64:65]
	v_and_b32_e32 v166, 0x70, v5
	v_mov_b32_e32 v167, v129
	v_lshl_add_u64 v[168:169], v[2:3], 0, v[166:167]
	v_mov_b64_e32 v[2:3], s[12:13]
	v_mad_i64_i32 v[2:3], s[12:13], v4, s27, v[2:3]
	s_mov_b32 s7, 0x58000
	v_lshl_add_u64 v[170:171], v[2:3], 0, v[166:167]
	v_add_co_u32_e32 v2, vcc, s7, v168
	v_ashrrev_i32_e32 v167, 8, v165
	s_nop 0
	v_addc_co_u32_e32 v3, vcc, 0, v169, vcc
	v_and_b32_e32 v174, 0xc0, v165
	v_and_b32_e32 v5, 31, v165
	v_lshlrev_b32_e32 v9, 5, v167
	global_load_dwordx4 v[130:133], v[168:169], off offset:512
	global_load_dwordx4 v[134:137], v[2:3], off offset:512
	global_load_dwordx4 v[138:141], v[170:171], off
	global_load_dwordx4 v[146:149], v[170:171], off offset:128
	v_add_u32_e32 v2, s8, v9
	v_or3_b32 v128, v174, s10, v5
	v_bfe_u32 v8, v165, 5, 1
	v_mad_u64_u32 v[0:1], s[10:11], v128, s23, v[0:1]
	v_ashrrev_i32_e32 v3, 31, v2
	v_lshl_add_u64 v[0:1], v[2:3], 1, v[0:1]
	v_lshlrev_b32_e32 v162, 4, v8
	v_mov_b32_e32 v163, v129
	v_lshl_add_u64 v[0:1], v[0:1], 0, v[162:163]
	s_mov_b32 s7, 0x2c000
	v_add_co_u32_e32 v2, vcc, s7, v0
	s_mov_b64 s[10:11], 0x2c000
	global_load_dwordx4 v[142:145], v[0:1], off
	v_addc_co_u32_e32 v3, vcc, 0, v1, vcc
	v_lshl_add_u64 v[6:7], v[0:1], 0, s[10:11]
	global_load_dwordx4 v[150:153], v[0:1], off offset:32
	global_load_dwordx4 v[154:157], v[6:7], off offset:32
	global_load_dwordx4 v[158:161], v[2:3], off
	s_movk_i32 s7, 0x90
	v_mul_lo_u32 v6, v4, s7
	s_movk_i32 s7, 0x78
	v_and_b32_e32 v3, 63, v165
	v_lshlrev_b32_e32 v164, 3, v8
	v_mul_lo_u32 v7, v4, s7
	v_mul_u32_u24_e32 v176, 0x90, v5
	v_mul_u32_u24_e32 v177, 0x108, v5
	v_add_u32_e32 v5, 0, v6
	v_lshlrev_b32_e32 v175, 2, v3
	v_or_b32_e32 v3, v164, v9
	v_add_u32_e32 v6, v5, v7
	s_movk_i32 s7, 0xff88
	s_waitcnt vmcnt(13)
	v_lshlrev_b32_e32 v178, 1, v3
	v_add_u32_e32 v3, v5, v166
	v_add_u32_e32 v5, v6, v166
	v_mad_u64_u32 v[172:173], s[10:11], v4, s7, v[6:7]
	v_add_u32_e32 v4, 0x4800, v5
	v_add_u32_e32 v5, 0x4880, v5
	v_add_u32_e32 v16, v172, v7
	v_mov_b32_e32 v14, v129
	v_mov_b32_e32 v15, v129
	v_mov_b32_e32 v0, v129
	v_mov_b32_e32 v1, v129
	v_mov_b32_e32 v2, v129
	v_mov_b32_e32 v6, v129
	v_mov_b32_e32 v7, v129
	v_mov_b32_e32 v8, v129
	v_mov_b32_e32 v9, v129
	s_waitcnt vmcnt(7)
	ds_write_b128 v3, v[130:133]
	s_waitcnt vmcnt(6)
	ds_write_b128 v3, v[134:137] offset:9216
	s_waitcnt vmcnt(5)
	ds_write2_b64 v4, v[138:139], v[140:141] offset1:1
	s_waitcnt vmcnt(4)
	ds_write2_b64 v5, v[146:147], v[148:149] offset1:1
	v_mov_b32_e32 v3, v129
	v_mov_b32_e32 v4, v129
	v_mov_b32_e32 v5, v129
	v_mov_b32_e32 v10, v129
	v_mov_b32_e32 v11, v129
	v_mov_b32_e32 v12, v129
	v_mov_b32_e32 v13, v129
	v_add_u32_e32 v173, v16, v166
	v_mov_b64_e32 v[30:31], v[14:15]
	v_mov_b64_e32 v[46:47], v[14:15]
	v_mov_b64_e32 v[62:63], v[14:15]
	s_mov_b32 s12, 0
	v_xor_b32_e32 v163, 0x80, v175
	s_mov_b64 s[10:11], -1
	v_mov_b32_e32 v184, 0
	v_mov_b32_e32 v182, 0xf149f2ca
	v_mov_b32_e32 v183, 0xf149f2ca
	v_mov_b32_e32 v179, 0
	v_mov_b64_e32 v[28:29], v[12:13]
	v_mov_b64_e32 v[26:27], v[10:11]
	v_mov_b64_e32 v[24:25], v[8:9]
	v_mov_b64_e32 v[22:23], v[6:7]
	v_mov_b64_e32 v[20:21], v[4:5]
	v_mov_b64_e32 v[18:19], v[2:3]
	v_mov_b64_e32 v[16:17], v[0:1]
	v_mov_b64_e32 v[44:45], v[12:13]
	v_mov_b64_e32 v[42:43], v[10:11]
	v_mov_b64_e32 v[40:41], v[8:9]
	v_mov_b64_e32 v[38:39], v[6:7]
	v_mov_b64_e32 v[36:37], v[4:5]
	v_mov_b64_e32 v[34:35], v[2:3]
	v_mov_b64_e32 v[32:33], v[0:1]
	v_mov_b64_e32 v[60:61], v[12:13]
	v_mov_b64_e32 v[58:59], v[10:11]
	v_mov_b64_e32 v[56:57], v[8:9]
	v_mov_b64_e32 v[54:55], v[6:7]
	v_mov_b64_e32 v[52:53], v[4:5]
	v_mov_b64_e32 v[50:51], v[2:3]
	v_mov_b64_e32 v[48:49], v[0:1]
	s_waitcnt lgkmcnt(0)
	s_waitcnt vmcnt(0)
	s_barrier
	v_mov_b32_e32 v236, 0
	v_mov_b32_e32 v237, 0
	v_mov_b32_e32 v238, 0
	v_mov_b32_e32 v239, 0
	v_mov_b32_e32 v240, 0
	v_mov_b32_e32 v241, 0
	v_mov_b32_e32 v242, 0
	v_mov_b32_e32 v243, 0
	v_mov_b32_e32 v244, 0
	v_mov_b32_e32 v245, 0
	v_mov_b32_e32 v246, 0
	v_mov_b32_e32 v247, 0
	v_mov_b32_e32 v248, 0
	v_mov_b32_e32 v249, 0
	v_mov_b32_e32 v250, 0
	v_mov_b32_e32 v251, 0
	s_branch .LBB0_384

; #define LAS __attribute__((address_space(3)))
; template <int DK, bool IS_A>
; __device__ __forceinline__ void attn_unit(const Params& P, int l, LAS unsigned char* lds, int b, int grp, int qtok0, int nkeys) {
;     ...
;             __builtin_amdgcn_s_setprio(1);
; #pragma unroll
;             for (int i = 0; i < DK / 16; ++i)
; #pragma unroll
;                 for (int jj = 0; jj < 2; ++jj) {
;                     const bf16x8 kf = *(const LAS bf16x8*)(kb + jj * 32 * AK_PITCH + i * 32);
;                     pa[jj] = __builtin_amdgcn_mfma_f32_32x32x16_bf16(kf, qa[i], pa[jj], 0, 0, 0);
;                     pb[jj] = __builtin_amdgcn_mfma_f32_32x32x16_bf16(kf, qb[i], pb[jj], 0, 0, 0);
;                 }
;             __builtin_amdgcn_s_setprio(0);
.LBB0_386:
	s_bitcmp1_b32 s12, 0
	s_cselect_b32 s10, 0x8a00, 0
	s_add_i32 s10, s10, 0
	v_add_u32_e32 v64, s10, v176
	v_add_u32_e32 v186, v64, v178
	s_setprio 1
	ds_read_b128 v[64:67], v186
	ds_read_b128 v[188:191], v186 offset:32
	s_waitcnt lgkmcnt(1)
	v_mfma_f32_32x32x16_bf16 v[112:127], v[64:67], v[142:145], v[236:251]
	v_mfma_f32_32x32x16_bf16 v[96:111], v[64:67], v[158:161], 0
	ds_read_b128 v[64:67], v186 offset:4608
	s_waitcnt lgkmcnt(1)
	v_mfma_f32_32x32x16_bf16 v[112:127], v[188:191], v[150:153], v[112:127]
	v_mfma_f32_32x32x16_bf16 v[96:111], v[188:191], v[154:157], v[96:111]
	ds_read_b128 v[188:191], v186 offset:4640
	s_waitcnt lgkmcnt(1)
	v_mfma_f32_32x32x16_bf16 v[80:95], v[64:67], v[142:145], v[236:251]
	v_mfma_f32_32x32x16_bf16 v[64:79], v[64:67], v[158:161], 0
	s_waitcnt lgkmcnt(0)
	v_mfma_f32_32x32x16_bf16 v[80:95], v[188:191], v[150:153], v[80:95]
	v_mfma_f32_32x32x16_bf16 v[64:79], v[188:191], v[154:157], v[64:79]
	s_setprio 0
	s_nop 9
	v_max_f32_e32 v180, v80, v80
	v_max_f32_e32 v181, v112, v112
	v_max_f32_e32 v180, v181, v180
	v_max3_f32 v181, v81, v114, v82
	v_max3_f32 v180, v180, v113, v115
	v_max3_f32 v181, v181, v116, v84
	v_max3_f32 v180, v180, v83, v117
	v_max3_f32 v181, v181, v118, v86
	v_max3_f32 v180, v180, v85, v119
	v_max3_f32 v181, v181, v120, v88
	v_max3_f32 v180, v180, v87, v121
	v_max3_f32 v181, v181, v122, v90
	v_max3_f32 v180, v180, v89, v123
	v_max3_f32 v181, v181, v124, v92
	v_max3_f32 v180, v180, v91, v125
	v_max3_f32 v181, v181, v126, v94
	v_max3_f32 v180, v180, v93, v127
	v_max3_f32 v180, v180, v95, v181
	v_sub_f32_e32 v180, v180, v236
	ds_bpermute_b32 v181, v163, v180
	s_waitcnt lgkmcnt(0)
	v_max3_f32 v187, v182, v180, v181
	v_add_f32_e32 v181, 0x41000000, v182
	v_cmp_gt_f32_e32 vcc, v187, v181
	s_cbranch_vccz .LBB0_388
	v_add_f32_e32 v181, v187, v236
	v_sub_f32_e32 v112, v112, v181
	v_sub_f32_e32 v113, v113, v181
	v_sub_f32_e32 v114, v114, v181
	v_sub_f32_e32 v115, v115, v181
	v_sub_f32_e32 v116, v116, v181
	v_sub_f32_e32 v117, v117, v181
	v_sub_f32_e32 v118, v118, v181
	v_sub_f32_e32 v119, v119, v181
	v_sub_f32_e32 v120, v120, v181
	v_sub_f32_e32 v121, v121, v181
	v_sub_f32_e32 v122, v122, v181
	v_sub_f32_e32 v123, v123, v181
	v_sub_f32_e32 v124, v124, v181
	v_sub_f32_e32 v125, v125, v181
	v_sub_f32_e32 v126, v126, v181
	v_sub_f32_e32 v127, v127, v181
	v_sub_f32_e32 v80, v80, v181
	v_sub_f32_e32 v81, v81, v181
	v_sub_f32_e32 v82, v82, v181
	v_sub_f32_e32 v83, v83, v181
	v_sub_f32_e32 v84, v84, v181
	v_sub_f32_e32 v85, v85, v181
	v_sub_f32_e32 v86, v86, v181
	v_sub_f32_e32 v87, v87, v181
	v_sub_f32_e32 v88, v88, v181
	v_sub_f32_e32 v89, v89, v181
	v_sub_f32_e32 v90, v90, v181
	v_sub_f32_e32 v91, v91, v181
	v_sub_f32_e32 v92, v92, v181
	v_sub_f32_e32 v93, v93, v181
	v_sub_f32_e32 v94, v94, v181
	v_sub_f32_e32 v95, v95, v181
	v_sub_f32_e32 v236, 0, v187
	v_sub_f32_e32 v237, 0, v187
	v_sub_f32_e32 v238, 0, v187
	v_sub_f32_e32 v239, 0, v187
	v_sub_f32_e32 v240, 0, v187
	v_sub_f32_e32 v241, 0, v187
	v_sub_f32_e32 v242, 0, v187
	v_sub_f32_e32 v243, 0, v187
	v_sub_f32_e32 v244, 0, v187
	v_sub_f32_e32 v245, 0, v187
	v_sub_f32_e32 v246, 0, v187
	v_sub_f32_e32 v247, 0, v187
	v_sub_f32_e32 v248, 0, v187
	v_sub_f32_e32 v249, 0, v187
	v_sub_f32_e32 v250, 0, v187
	v_sub_f32_e32 v251, 0, v187
	v_sub_f32_e32 v180, v182, v187
	v_exp_f32_e32 v180, v180
	s_nop 0
	v_pk_mul_f32 v[62:63], v[62:63], v[180:181] op_sel_hi:[1,0]
	v_pk_mul_f32 v[60:61], v[60:61], v[180:181] op_sel_hi:[1,0]
	v_pk_mul_f32 v[58:59], v[58:59], v[180:181] op_sel_hi:[1,0]
	v_pk_mul_f32 v[56:57], v[56:57], v[180:181] op_sel_hi:[1,0]
	v_pk_mul_f32 v[54:55], v[54:55], v[180:181] op_sel_hi:[1,0]
	v_pk_mul_f32 v[52:53], v[52:53], v[180:181] op_sel_hi:[1,0]
	v_pk_mul_f32 v[50:51], v[50:51], v[180:181] op_sel_hi:[1,0]
	v_pk_mul_f32 v[48:49], v[48:49], v[180:181] op_sel_hi:[1,0]
	v_pk_mul_f32 v[46:47], v[46:47], v[180:181] op_sel_hi:[1,0]
	v_pk_mul_f32 v[44:45], v[44:45], v[180:181] op_sel_hi:[1,0]
	v_pk_mul_f32 v[42:43], v[42:43], v[180:181] op_sel_hi:[1,0]
	v_pk_mul_f32 v[40:41], v[40:41], v[180:181] op_sel_hi:[1,0]
	v_pk_mul_f32 v[38:39], v[38:39], v[180:181] op_sel_hi:[1,0]
	v_pk_mul_f32 v[36:37], v[36:37], v[180:181] op_sel_hi:[1,0]
	v_pk_mul_f32 v[34:35], v[34:35], v[180:181] op_sel_hi:[1,0]
	v_pk_mul_f32 v[32:33], v[32:33], v[180:181] op_sel_hi:[1,0]
	v_mul_f32_e32 v184, v184, v180
	s_branch .LBB0_389

; #define LAS __attribute__((address_space(3)))
; __device__ __forceinline__ unsigned pk2(float lo, float hi) { f32x2_t v = {lo, hi}; bf16x2_t b = __builtin_convertvector(v, bf16x2_t); return __builtin_bit_cast(unsigned, b); }
; template <int DK, bool IS_A>
; __device__ __forceinline__ void attn_unit(const Params& P, int l, LAS unsigned char* lds, int b, int grp, int qtok0, int nkeys) {
;     ...
;             AT_SOFTMAX(pa, ma, la, oa0, oa1);
;             AT_SOFTMAX(pb, mb, lb_, ob0, ob1);
;     ...
; #pragma unroll
;             for (int ks = 0; ks < 4; ++ks) {
;                 const int o8 = 8 * (ks & 1);
;                 u32x4 w; const f32x16& xa = pa[ks >> 1]; const f32x16& xb = pb[ks >> 1];
;                 w.x = pk2(xa[o8], xa[o8 + 1]); w.y = pk2(xa[o8 + 2], xa[o8 + 3]); w.z = pk2(xa[o8 + 4], xa[o8 + 5]); w.w = pk2(xa[o8 + 6], xa[o8 + 7]);
;                 const bf16x8 pfa = __builtin_bit_cast(bf16x8, w);
;                 w.x = pk2(xb[o8], xb[o8 + 1]); w.y = pk2(xb[o8 + 2], xb[o8 + 3]); w.z = pk2(xb[o8 + 4], xb[o8 + 5]); w.w = pk2(xb[o8 + 6], xb[o8 + 7]);
;                 const bf16x8 pfb = __builtin_bit_cast(bf16x8, w);
;                 const u32x2 a0 = *(const LAS u32x2*)(vb + ks * 32), a1 = *(const LAS u32x2*)(vb + ks * 32 + 16);
;                 const u32x2 c0 = *(const LAS u32x2*)(vb + 32 * AV_PITCH + ks * 32), c1 = *(const LAS u32x2*)(vb + 32 * AV_PITCH + ks * 32 + 16);
;                 const bf16x8 v0 = __builtin_bit_cast(bf16x8, ((u32x4){a0.x, a0.y, a1.x, a1.y})), v1 = __builtin_bit_cast(bf16x8, ((u32x4){c0.x, c0.y, c1.x, c1.y}));
;                 oa0 = __builtin_amdgcn_mfma_f32_32x32x16_bf16(v0, pfa, oa0, 0, 0, 0);
;                 oa1 = __builtin_amdgcn_mfma_f32_32x32x16_bf16(v1, pfa, oa1, 0, 0, 0);
;                 ob0 = __builtin_amdgcn_mfma_f32_32x32x16_bf16(v0, pfb, ob0, 0, 0, 0);
;                 ob1 = __builtin_amdgcn_mfma_f32_32x32x16_bf16(v1, pfb, ob1, 0, 0, 0);
;             }
.LBB0_392:
	v_exp_f32_e32 v112, v112
	v_exp_f32_e32 v113, v113
	v_exp_f32_e32 v114, v114
	v_exp_f32_e32 v115, v115
	v_add_f32_e32 v180, 0, v112
	v_exp_f32_e32 v116, v116
	v_add_f32_e32 v180, v113, v180
	v_exp_f32_e32 v117, v117
	v_add_f32_e32 v180, v114, v180
	v_exp_f32_e32 v118, v118
	v_add_f32_e32 v180, v115, v180
	v_exp_f32_e32 v119, v119
	v_add_f32_e32 v180, v116, v180
	v_exp_f32_e32 v120, v120
	v_add_f32_e32 v180, v117, v180
	v_exp_f32_e32 v121, v121
	v_add_f32_e32 v180, v118, v180
	v_exp_f32_e32 v122, v122
	v_add_f32_e32 v180, v119, v180
	v_exp_f32_e32 v123, v123
	v_add_f32_e32 v180, v120, v180
	v_exp_f32_e32 v124, v124
	v_add_f32_e32 v180, v121, v180
	v_exp_f32_e32 v125, v125
	v_add_f32_e32 v180, v122, v180
	v_exp_f32_e32 v126, v126
	v_add_f32_e32 v180, v123, v180
	v_exp_f32_e32 v127, v127
	v_add_f32_e32 v180, v124, v180
	v_exp_f32_e32 v182, v80
	v_add_f32_e32 v180, v125, v180
	v_exp_f32_e32 v210, v81
	v_add_f32_e32 v80, v126, v180
	v_exp_f32_e32 v211, v82
	v_add_f32_e32 v80, v127, v80
	v_exp_f32_e32 v212, v83
	v_add_f32_e32 v80, v182, v80
	v_exp_f32_e32 v213, v84
	v_add_f32_e32 v80, v210, v80
	v_exp_f32_e32 v214, v85
	v_add_f32_e32 v80, v211, v80
	v_exp_f32_e32 v215, v86
	v_add_f32_e32 v80, v212, v80
	v_exp_f32_e32 v216, v87
	v_add_f32_e32 v80, v213, v80
	v_exp_f32_e32 v217, v88
	v_add_f32_e32 v80, v214, v80
	v_exp_f32_e32 v219, v89
	v_add_f32_e32 v80, v215, v80
	v_add_f32_e32 v80, v216, v80
	v_add_f32_e32 v80, v217, v80
	v_add_f32_e32 v223, v219, v80
	v_exp_f32_e32 v224, v90
	v_exp_f32_e32 v225, v91
	v_exp_f32_e32 v92, v92
	v_add_u32_e32 v80, s10, v177
	v_sub_f32_e32 v81, v96, v185
	v_add_u32_e32 v88, v80, v164
	v_exp_f32_e32 v183, v81
	v_sub_f32_e32 v81, v97, v185
	v_add_u32_e32 v180, 0x4800, v88
	v_add_u32_e32 v181, 0x6800, v88
	v_exp_f32_e32 v188, v81
	ds_read2_b64 v[80:83], v180 offset1:2
	ds_read2_b64 v[88:91], v181 offset0:32 offset1:34
	v_sub_f32_e32 v96, v99, v185
	v_sub_f32_e32 v84, v98, v185
	v_exp_f32_e32 v190, v96
	v_sub_f32_e32 v96, v100, v185
	v_exp_f32_e32 v189, v84
	v_cvt_pk_bf16_f32 v84, v112, v113
	v_cvt_pk_bf16_f32 v85, v114, v115
	v_cvt_pk_bf16_f32 v86, v116, v117
	v_cvt_pk_bf16_f32 v87, v118, v119
	v_exp_f32_e32 v191, v96
	v_sub_f32_e32 v96, v101, v185
	s_waitcnt lgkmcnt(1)
	v_mfma_f32_32x32x16_bf16 v[48:63], v[80:83], v[84:87], v[48:63]
	v_exp_f32_e32 v192, v96
	v_sub_f32_e32 v96, v102, v185
	v_exp_f32_e32 v193, v96
	v_sub_f32_e32 v96, v107, v185
	v_exp_f32_e32 v198, v96
	v_sub_f32_e32 v96, v108, v185
	v_exp_f32_e32 v199, v96
	s_waitcnt lgkmcnt(0)
	v_mfma_f32_32x32x16_bf16 v[32:47], v[88:91], v[84:87], v[32:47]
	v_sub_f32_e32 v84, v103, v185
	v_exp_f32_e32 v194, v84
	v_cvt_pk_bf16_f32 v84, v183, v188
	v_cvt_pk_bf16_f32 v85, v189, v190
	v_cvt_pk_bf16_f32 v86, v191, v192
	v_cvt_pk_bf16_f32 v87, v193, v194
	v_sub_f32_e32 v96, v109, v185
	v_exp_f32_e32 v204, v96
	v_mfma_f32_32x32x16_bf16 v[16:31], v[80:83], v[84:87], v[16:31]
	v_exp_f32_e32 v93, v93
	v_sub_f32_e32 v80, v104, v185
	v_exp_f32_e32 v195, v80
	v_sub_f32_e32 v80, v105, v185
	v_exp_f32_e32 v196, v80
	ds_read2_b64 v[80:83], v180 offset0:4 offset1:6
	v_mfma_f32_32x32x16_bf16 v[0:15], v[88:91], v[84:87], v[0:15]
	ds_read2_b64 v[88:91], v181 offset0:36 offset1:38
	v_sub_f32_e32 v84, v106, v185
	v_exp_f32_e32 v197, v84
	v_cvt_pk_bf16_f32 v84, v120, v121
	v_cvt_pk_bf16_f32 v85, v122, v123
	v_cvt_pk_bf16_f32 v86, v124, v125
	v_cvt_pk_bf16_f32 v87, v126, v127
	v_sub_f32_e32 v96, v110, v185
	v_exp_f32_e32 v205, v96
	s_waitcnt lgkmcnt(1)
	v_mfma_f32_32x32x16_bf16 v[48:63], v[80:83], v[84:87], v[48:63]
	v_sub_f32_e32 v64, v64, v185
	v_exp_f32_e32 v207, v64
	v_sub_f32_e32 v64, v65, v185
	v_exp_f32_e32 v208, v64
	v_sub_f32_e32 v64, v66, v185
	v_exp_f32_e32 v209, v64
	v_sub_f32_e32 v64, v67, v185
	s_waitcnt lgkmcnt(0)
	v_mfma_f32_32x32x16_bf16 v[32:47], v[88:91], v[84:87], v[32:47]
	v_sub_f32_e32 v84, v111, v185
	v_exp_f32_e32 v206, v84
	v_cvt_pk_bf16_f32 v84, v195, v196
	v_cvt_pk_bf16_f32 v85, v197, v198
	v_cvt_pk_bf16_f32 v86, v199, v204
	v_cvt_pk_bf16_f32 v87, v205, v206
	s_nop 1
	s_nop 1
	v_mfma_f32_32x32x16_bf16 v[16:31], v[80:83], v[84:87], v[16:31]
	v_exp_f32_e32 v94, v94
	ds_read2_b64 v[80:83], v180 offset0:8 offset1:10
	v_mfma_f32_32x32x16_bf16 v[0:15], v[88:91], v[84:87], v[0:15]
	ds_read2_b64 v[88:91], v181 offset0:40 offset1:42
	v_cvt_pk_bf16_f32 v84, v182, v210
	v_exp_f32_e32 v210, v64
	v_sub_f32_e32 v64, v68, v185
	v_cvt_pk_bf16_f32 v85, v211, v212
	v_exp_f32_e32 v211, v64
	v_sub_f32_e32 v64, v69, v185
	v_exp_f32_e32 v212, v64
	v_sub_f32_e32 v64, v70, v185
	v_cvt_pk_bf16_f32 v86, v213, v214
	v_exp_f32_e32 v213, v64
	v_sub_f32_e32 v64, v71, v185
	v_exp_f32_e32 v214, v64
	v_cvt_pk_bf16_f32 v87, v215, v216
	v_cvt_pk_bf16_f32 v64, v207, v208
	s_waitcnt lgkmcnt(1)
	v_mfma_f32_32x32x16_bf16 v[48:63], v[80:83], v[84:87], v[48:63]
	v_cvt_pk_bf16_f32 v65, v209, v210
	v_cvt_pk_bf16_f32 v66, v211, v212
	v_cvt_pk_bf16_f32 v67, v213, v214
	s_waitcnt lgkmcnt(0)
	v_mfma_f32_32x32x16_bf16 v[32:47], v[88:91], v[84:87], v[32:47]
	v_exp_f32_e32 v84, v95
	v_sub_f32_e32 v68, v72, v185
	v_exp_f32_e32 v215, v68
	v_sub_f32_e32 v68, v73, v185
	v_exp_f32_e32 v216, v68
	ds_read2_b64 v[68:71], v180 offset0:12 offset1:14
	v_sub_f32_e32 v72, v75, v185
	v_mfma_f32_32x32x16_bf16 v[16:31], v[80:83], v[64:67], v[16:31]
	ds_read2_b64 v[80:83], v181 offset0:44 offset1:46
	v_exp_f32_e32 v221, v72
	v_sub_f32_e32 v72, v76, v185
	v_exp_f32_e32 v222, v72
	v_sub_f32_e32 v72, v77, v185
	v_mfma_f32_32x32x16_bf16 v[0:15], v[88:91], v[64:67], v[0:15]
	v_sub_f32_e32 v64, v74, v185
	v_exp_f32_e32 v218, v64
	v_cvt_pk_bf16_f32 v64, v217, v219
	v_cvt_pk_bf16_f32 v65, v224, v225
	v_cvt_pk_bf16_f32 v66, v92, v93
	v_cvt_pk_bf16_f32 v67, v94, v84
	v_exp_f32_e32 v217, v72
	v_sub_f32_e32 v72, v78, v185
	s_waitcnt lgkmcnt(1)
; #define LAS __attribute__((address_space(3)))
; __device__ __forceinline__ unsigned pk2(float lo, float hi) { f32x2_t v = {lo, hi}; bf16x2_t b = __builtin_convertvector(v, bf16x2_t); return __builtin_bit_cast(unsigned, b); }
; template <int DK, bool IS_A>
; __device__ __forceinline__ void attn_unit(const Params& P, int l, LAS unsigned char* lds, int b, int grp, int qtok0, int nkeys) {
;     ...
;             __builtin_amdgcn_s_setprio(1);
; #pragma unroll
;             for (int i = 0; i < DK / 16; ++i)
; #pragma unroll
;                 for (int jj = 0; jj < 2; ++jj) {
;                     const bf16x8 kf = *(const LAS bf16x8*)(kb + jj * 32 * AK_PITCH + i * 32);
;                     pa[jj] = __builtin_amdgcn_mfma_f32_32x32x16_bf16(kf, qa[i], pa[jj], 0, 0, 0);
;                     pb[jj] = __builtin_amdgcn_mfma_f32_32x32x16_bf16(kf, qb[i], pb[jj], 0, 0, 0);
;                 }
;             __builtin_amdgcn_s_setprio(0);
;     ...
;             for (int ks = 0; ks < 4; ++ks) {
;                 const int o8 = 8 * (ks & 1);
;                 u32x4 w; const f32x16& xa = pa[ks >> 1]; const f32x16& xb = pb[ks >> 1];
;                 w.x = pk2(xa[o8], xa[o8 + 1]); w.y = pk2(xa[o8 + 2], xa[o8 + 3]); w.z = pk2(xa[o8 + 4], xa[o8 + 5]); w.w = pk2(xa[o8 + 6], xa[o8 + 7]);
;                 const bf16x8 pfa = __builtin_bit_cast(bf16x8, w);
;                 w.x = pk2(xb[o8], xb[o8 + 1]); w.y = pk2(xb[o8 + 2], xb[o8 + 3]); w.z = pk2(xb[o8 + 4], xb[o8 + 5]); w.w = pk2(xb[o8 + 6], xb[o8 + 7]);
;                 const bf16x8 pfb = __builtin_bit_cast(bf16x8, w);
;                 const u32x2 a0 = *(const LAS u32x2*)(vb + ks * 32), a1 = *(const LAS u32x2*)(vb + ks * 32 + 16);
;                 const u32x2 c0 = *(const LAS u32x2*)(vb + 32 * AV_PITCH + ks * 32), c1 = *(const LAS u32x2*)(vb + 32 * AV_PITCH + ks * 32 + 16);
;                 const bf16x8 v0 = __builtin_bit_cast(bf16x8, ((u32x4){a0.x, a0.y, a1.x, a1.y})), v1 = __builtin_bit_cast(bf16x8, ((u32x4){c0.x, c0.y, c1.x, c1.y}));
;                 oa0 = __builtin_amdgcn_mfma_f32_32x32x16_bf16(v0, pfa, oa0, 0, 0, 0);
;                 oa1 = __builtin_amdgcn_mfma_f32_32x32x16_bf16(v1, pfa, oa1, 0, 0, 0);
;                 ob0 = __builtin_amdgcn_mfma_f32_32x32x16_bf16(v0, pfb, ob0, 0, 0, 0);
;                 ob1 = __builtin_amdgcn_mfma_f32_32x32x16_bf16(v1, pfb, ob1, 0, 0, 0);
;             }
	v_mfma_f32_32x32x16_bf16 v[48:63], v[68:71], v[64:67], v[48:63]
	v_exp_f32_e32 v219, v72
	s_waitcnt lgkmcnt(0)
	v_mfma_f32_32x32x16_bf16 v[32:47], v[80:83], v[64:67], v[32:47]
	v_sub_f32_e32 v64, v79, v185
	v_exp_f32_e32 v220, v64
	v_cvt_pk_bf16_f32 v64, v215, v216
	v_cvt_pk_bf16_f32 v65, v218, v221
	v_cvt_pk_bf16_f32 v66, v222, v217
	v_cvt_pk_bf16_f32 v67, v219, v220
	s_nop 1
	s_nop 1
	v_mfma_f32_32x32x16_bf16 v[16:31], v[68:71], v[64:67], v[16:31]
	v_add_f32_e32 v68, v224, v223
	v_add_f32_e32 v68, v225, v68
	v_add_f32_e32 v68, v92, v68
	v_add_f32_e32 v68, v93, v68
	v_add_f32_e32 v68, v94, v68
	v_add_f32_e32 v68, v84, v68
	v_add_f32_e32 v184, v184, v68
	v_mfma_f32_32x32x16_bf16 v[0:15], v[80:83], v[64:67], v[0:15]
	s_setprio 1
	ds_read_b128 v[64:67], v186 offset:9216
	ds_read_b128 v[224:227], v186 offset:9248
	s_waitcnt lgkmcnt(1)
	v_mfma_f32_32x32x16_bf16 v[112:127], v[64:67], v[142:145], v[236:251]
	v_mfma_f32_32x32x16_bf16 v[96:111], v[64:67], v[158:161], 0
	ds_read_b128 v[64:67], v186 offset:13824
	s_waitcnt lgkmcnt(1)
	v_mfma_f32_32x32x16_bf16 v[112:127], v[224:227], v[150:153], v[112:127]
	v_mfma_f32_32x32x16_bf16 v[96:111], v[224:227], v[154:157], v[96:111]
	ds_read_b128 v[224:227], v186 offset:13856
	s_waitcnt lgkmcnt(1)
	v_mfma_f32_32x32x16_bf16 v[80:95], v[64:67], v[142:145], v[236:251]
	v_mfma_f32_32x32x16_bf16 v[64:79], v[64:67], v[158:161], 0
	s_waitcnt lgkmcnt(0)
	v_mfma_f32_32x32x16_bf16 v[80:95], v[224:227], v[150:153], v[80:95]
	v_mfma_f32_32x32x16_bf16 v[64:79], v[224:227], v[154:157], v[64:79]
	s_setprio 0
	s_nop 9
	v_max_f32_e32 v182, v80, v80
	v_max_f32_e32 v186, v112, v112
	v_max_f32_e32 v182, v186, v182
	v_max3_f32 v186, v81, v114, v82
	v_max3_f32 v182, v182, v113, v115
	v_max3_f32 v186, v186, v116, v84
	v_max3_f32 v182, v182, v83, v117
	v_max3_f32 v186, v186, v118, v86
	v_max3_f32 v182, v182, v85, v119
	v_max3_f32 v186, v186, v120, v88
	v_max3_f32 v182, v182, v87, v121
	v_max3_f32 v186, v186, v122, v90
	v_max3_f32 v182, v182, v89, v123
	v_max3_f32 v186, v186, v124, v92
	v_max3_f32 v182, v182, v91, v125
	v_max3_f32 v186, v186, v126, v94
	v_max3_f32 v182, v182, v93, v127
	v_max3_f32 v182, v182, v95, v186
	v_sub_f32_e32 v182, v182, v236
	ds_bpermute_b32 v186, v163, v182
	s_waitcnt lgkmcnt(0)
	v_max3_f32 v182, v187, v182, v186
	v_add_f32_e32 v186, 0x41000000, v187
	v_cmp_gt_f32_e32 vcc, v182, v186
	s_cbranch_vccz .LBB0_394
	v_add_f32_e32 v186, v182, v236
	v_sub_f32_e32 v112, v112, v186
	v_sub_f32_e32 v113, v113, v186
	v_sub_f32_e32 v114, v114, v186
	v_sub_f32_e32 v115, v115, v186
	v_sub_f32_e32 v116, v116, v186
	v_sub_f32_e32 v117, v117, v186
	v_sub_f32_e32 v118, v118, v186
	v_sub_f32_e32 v119, v119, v186
	v_sub_f32_e32 v120, v120, v186
	v_sub_f32_e32 v121, v121, v186
	v_sub_f32_e32 v122, v122, v186
	v_sub_f32_e32 v123, v123, v186
	v_sub_f32_e32 v124, v124, v186
	v_sub_f32_e32 v125, v125, v186
	v_sub_f32_e32 v126, v126, v186
	v_sub_f32_e32 v127, v127, v186
	v_sub_f32_e32 v80, v80, v186
	v_sub_f32_e32 v81, v81, v186
	v_sub_f32_e32 v82, v82, v186
	v_sub_f32_e32 v83, v83, v186
	v_sub_f32_e32 v84, v84, v186
	v_sub_f32_e32 v85, v85, v186
	v_sub_f32_e32 v86, v86, v186
	v_sub_f32_e32 v87, v87, v186
	v_sub_f32_e32 v88, v88, v186
	v_sub_f32_e32 v89, v89, v186
	v_sub_f32_e32 v90, v90, v186
	v_sub_f32_e32 v91, v91, v186
	v_sub_f32_e32 v92, v92, v186
	v_sub_f32_e32 v93, v93, v186
	v_sub_f32_e32 v94, v94, v186
	v_sub_f32_e32 v95, v95, v186
	v_sub_f32_e32 v236, 0, v182
	v_sub_f32_e32 v237, 0, v182
	v_sub_f32_e32 v238, 0, v182
	v_sub_f32_e32 v239, 0, v182
	v_sub_f32_e32 v240, 0, v182
	v_sub_f32_e32 v241, 0, v182
	v_sub_f32_e32 v242, 0, v182
	v_sub_f32_e32 v243, 0, v182
	v_sub_f32_e32 v244, 0, v182
	v_sub_f32_e32 v245, 0, v182
	v_sub_f32_e32 v246, 0, v182
	v_sub_f32_e32 v247, 0, v182
	v_sub_f32_e32 v248, 0, v182
	v_sub_f32_e32 v249, 0, v182
	v_sub_f32_e32 v250, 0, v182
	v_sub_f32_e32 v251, 0, v182
	v_sub_f32_e32 v186, v187, v182
	v_exp_f32_e32 v186, v186
	s_nop 0
	v_pk_mul_f32 v[62:63], v[62:63], v[186:187] op_sel_hi:[1,0]
	v_pk_mul_f32 v[60:61], v[60:61], v[186:187] op_sel_hi:[1,0]
	v_pk_mul_f32 v[58:59], v[58:59], v[186:187] op_sel_hi:[1,0]
	v_pk_mul_f32 v[56:57], v[56:57], v[186:187] op_sel_hi:[1,0]
	v_pk_mul_f32 v[54:55], v[54:55], v[186:187] op_sel_hi:[1,0]
	v_pk_mul_f32 v[52:53], v[52:53], v[186:187] op_sel_hi:[1,0]
	v_pk_mul_f32 v[50:51], v[50:51], v[186:187] op_sel_hi:[1,0]
	v_pk_mul_f32 v[48:49], v[48:49], v[186:187] op_sel_hi:[1,0]
	v_pk_mul_f32 v[46:47], v[46:47], v[186:187] op_sel_hi:[1,0]
	v_pk_mul_f32 v[44:45], v[44:45], v[186:187] op_sel_hi:[1,0]
	v_pk_mul_f32 v[42:43], v[42:43], v[186:187] op_sel_hi:[1,0]
	v_pk_mul_f32 v[40:41], v[40:41], v[186:187] op_sel_hi:[1,0]
	v_pk_mul_f32 v[38:39], v[38:39], v[186:187] op_sel_hi:[1,0]
	v_pk_mul_f32 v[36:37], v[36:37], v[186:187] op_sel_hi:[1,0]
	v_pk_mul_f32 v[34:35], v[34:35], v[186:187] op_sel_hi:[1,0]
	v_pk_mul_f32 v[32:33], v[32:33], v[186:187] op_sel_hi:[1,0]
	v_mul_f32_e32 v184, v184, v186
	s_branch .LBB0_395

; #define LAS __attribute__((address_space(3)))
; __device__ __forceinline__ unsigned pk2(float lo, float hi) { f32x2_t v = {lo, hi}; bf16x2_t b = __builtin_convertvector(v, bf16x2_t); return __builtin_bit_cast(unsigned, b); }
; template <int DK, bool IS_A>
; __device__ __forceinline__ void attn_unit(const Params& P, int l, LAS unsigned char* lds, int b, int grp, int qtok0, int nkeys) {
;     ...
;             AT_SOFTMAX(pa, ma, la, oa0, oa1);
;             AT_SOFTMAX(pb, mb, lb_, ob0, ob1);
;     ...
; #pragma unroll
;             for (int ks = 0; ks < 4; ++ks) {
;                 const int o8 = 8 * (ks & 1);
;                 u32x4 w; const f32x16& xa = pa[ks >> 1]; const f32x16& xb = pb[ks >> 1];
;                 w.x = pk2(xa[o8], xa[o8 + 1]); w.y = pk2(xa[o8 + 2], xa[o8 + 3]); w.z = pk2(xa[o8 + 4], xa[o8 + 5]); w.w = pk2(xa[o8 + 6], xa[o8 + 7]);
;                 const bf16x8 pfa = __builtin_bit_cast(bf16x8, w);
;                 w.x = pk2(xb[o8], xb[o8 + 1]); w.y = pk2(xb[o8 + 2], xb[o8 + 3]); w.z = pk2(xb[o8 + 4], xb[o8 + 5]); w.w = pk2(xb[o8 + 6], xb[o8 + 7]);
;                 const bf16x8 pfb = __builtin_bit_cast(bf16x8, w);
;                 const u32x2 a0 = *(const LAS u32x2*)(vb + ks * 32), a1 = *(const LAS u32x2*)(vb + ks * 32 + 16);
;                 const u32x2 c0 = *(const LAS u32x2*)(vb + 32 * AV_PITCH + ks * 32), c1 = *(const LAS u32x2*)(vb + 32 * AV_PITCH + ks * 32 + 16);
;                 const bf16x8 v0 = __builtin_bit_cast(bf16x8, ((u32x4){a0.x, a0.y, a1.x, a1.y})), v1 = __builtin_bit_cast(bf16x8, ((u32x4){c0.x, c0.y, c1.x, c1.y}));
;                 oa0 = __builtin_amdgcn_mfma_f32_32x32x16_bf16(v0, pfa, oa0, 0, 0, 0);
;                 oa1 = __builtin_amdgcn_mfma_f32_32x32x16_bf16(v1, pfa, oa1, 0, 0, 0);
;                 ob0 = __builtin_amdgcn_mfma_f32_32x32x16_bf16(v0, pfb, ob0, 0, 0, 0);
;                 ob1 = __builtin_amdgcn_mfma_f32_32x32x16_bf16(v1, pfb, ob1, 0, 0, 0);
;             }
;         }
;         if (t + 1 < NT) AT_STORE(buf ^ 1);
;         __syncthreads();
;     }
.LBB0_398:
	ds_read2_b64 v[186:189], v180 offset0:16 offset1:18
	ds_read2_b64 v[194:197], v181 offset0:48 offset1:50
	v_exp_f32_e32 v112, v112
	v_exp_f32_e32 v113, v113
	v_exp_f32_e32 v114, v114
	v_exp_f32_e32 v115, v115
	v_exp_f32_e32 v116, v116
	v_exp_f32_e32 v117, v117
	v_exp_f32_e32 v118, v118
	v_exp_f32_e32 v119, v119
	v_sub_f32_e32 v96, v96, v183
	v_sub_f32_e32 v97, v97, v183
	v_sub_f32_e32 v98, v98, v183
	v_sub_f32_e32 v99, v99, v183
	v_sub_f32_e32 v100, v100, v183
	v_sub_f32_e32 v101, v101, v183
	v_sub_f32_e32 v102, v102, v183
	v_sub_f32_e32 v103, v103, v183
	v_exp_f32_e32 v96, v96
	v_exp_f32_e32 v97, v97
	v_exp_f32_e32 v98, v98
	v_exp_f32_e32 v99, v99
	v_exp_f32_e32 v100, v100
	v_exp_f32_e32 v101, v101
	v_exp_f32_e32 v102, v102
	v_exp_f32_e32 v103, v103
	v_cvt_pk_bf16_f32 v190, v112, v113
	v_cvt_pk_bf16_f32 v191, v114, v115
	v_cvt_pk_bf16_f32 v192, v116, v117
	v_cvt_pk_bf16_f32 v193, v118, v119
	s_waitcnt lgkmcnt(1)
	s_nop 1
	v_mfma_f32_32x32x16_bf16 v[48:63], v[186:189], v[190:193], v[48:63]
	v_exp_f32_e32 v120, v120
	s_waitcnt lgkmcnt(0)
	v_mfma_f32_32x32x16_bf16 v[32:47], v[194:197], v[190:193], v[32:47]
	v_cvt_pk_bf16_f32 v190, v96, v97
	v_cvt_pk_bf16_f32 v191, v98, v99
	v_cvt_pk_bf16_f32 v192, v100, v101
	v_cvt_pk_bf16_f32 v193, v102, v103
	v_exp_f32_e32 v121, v121
	v_exp_f32_e32 v122, v122
	v_exp_f32_e32 v123, v123
	v_mfma_f32_32x32x16_bf16 v[16:31], v[186:189], v[190:193], v[16:31]
	ds_read2_b64 v[186:189], v180 offset0:20 offset1:22
	v_exp_f32_e32 v124, v124
	v_exp_f32_e32 v125, v125
	v_exp_f32_e32 v126, v126
	v_exp_f32_e32 v127, v127
	v_sub_f32_e32 v104, v104, v183
	v_sub_f32_e32 v105, v105, v183
	v_mfma_f32_32x32x16_bf16 v[0:15], v[194:197], v[190:193], v[0:15]
	ds_read2_b64 v[194:197], v181 offset0:52 offset1:54
	v_sub_f32_e32 v106, v106, v183
	v_sub_f32_e32 v107, v107, v183
	v_sub_f32_e32 v108, v108, v183
	v_sub_f32_e32 v109, v109, v183
	v_sub_f32_e32 v110, v110, v183
	v_sub_f32_e32 v111, v111, v183
	v_exp_f32_e32 v104, v104
	v_exp_f32_e32 v105, v105
	v_exp_f32_e32 v106, v106
	v_exp_f32_e32 v107, v107
	v_exp_f32_e32 v108, v108
	v_exp_f32_e32 v109, v109
	v_exp_f32_e32 v110, v110
	v_exp_f32_e32 v111, v111
	v_cvt_pk_bf16_f32 v190, v120, v121
	v_cvt_pk_bf16_f32 v191, v122, v123
	v_cvt_pk_bf16_f32 v192, v124, v125
	v_cvt_pk_bf16_f32 v193, v126, v127
	v_sub_f32_e32 v66, v66, v183
	v_exp_f32_e32 v185, v66
	s_waitcnt lgkmcnt(1)
	v_mfma_f32_32x32x16_bf16 v[48:63], v[186:189], v[190:193], v[48:63]
	v_sub_f32_e32 v66, v67, v183
	v_exp_f32_e32 v67, v66
	v_sub_f32_e32 v66, v68, v183
	v_exp_f32_e32 v68, v66
	v_sub_f32_e32 v66, v69, v183
	s_waitcnt lgkmcnt(0)
	v_mfma_f32_32x32x16_bf16 v[32:47], v[194:197], v[190:193], v[32:47]
	v_cvt_pk_bf16_f32 v190, v104, v105
	v_cvt_pk_bf16_f32 v191, v106, v107
	v_cvt_pk_bf16_f32 v192, v108, v109
	v_cvt_pk_bf16_f32 v193, v110, v111
	s_nop 1
	v_mfma_f32_32x32x16_bf16 v[16:31], v[186:189], v[190:193], v[16:31]
	ds_read2_b64 v[186:189], v180 offset0:24 offset1:26
	v_exp_f32_e32 v69, v66
	v_sub_f32_e32 v66, v70, v183
	v_exp_f32_e32 v80, v80
	v_mfma_f32_32x32x16_bf16 v[0:15], v[194:197], v[190:193], v[0:15]
	ds_read2_b64 v[194:197], v181 offset0:56 offset1:58
	v_exp_f32_e32 v81, v81
	v_exp_f32_e32 v82, v82
	v_exp_f32_e32 v83, v83
	v_exp_f32_e32 v84, v84
	v_exp_f32_e32 v85, v85
	v_exp_f32_e32 v86, v86
	v_exp_f32_e32 v87, v87
	v_sub_f32_e32 v64, v64, v183
	v_sub_f32_e32 v65, v65, v183
	v_exp_f32_e32 v70, v66
	v_sub_f32_e32 v66, v71, v183
	v_exp_f32_e32 v64, v64
	v_exp_f32_e32 v65, v65
	v_exp_f32_e32 v71, v66
	v_cvt_pk_bf16_f32 v190, v80, v81
	v_cvt_pk_bf16_f32 v191, v82, v83
	v_cvt_pk_bf16_f32 v192, v84, v85
	v_cvt_pk_bf16_f32 v193, v86, v87
	s_waitcnt lgkmcnt(1)
	s_nop 1
	v_mfma_f32_32x32x16_bf16 v[48:63], v[186:189], v[190:193], v[48:63]
	v_exp_f32_e32 v88, v88
	s_waitcnt lgkmcnt(0)
	v_mfma_f32_32x32x16_bf16 v[32:47], v[194:197], v[190:193], v[32:47]
	v_cvt_pk_bf16_f32 v190, v64, v65
	v_cvt_pk_bf16_f32 v191, v185, v67
	v_cvt_pk_bf16_f32 v192, v68, v69
	v_cvt_pk_bf16_f32 v193, v70, v71
	v_exp_f32_e32 v89, v89
	v_exp_f32_e32 v90, v90
	v_exp_f32_e32 v91, v91
	v_mfma_f32_32x32x16_bf16 v[16:31], v[186:189], v[190:193], v[16:31]
	ds_read2_b64 v[186:189], v180 offset0:28 offset1:30
	v_exp_f32_e32 v92, v92
	v_exp_f32_e32 v93, v93
	v_exp_f32_e32 v94, v94
	v_exp_f32_e32 v66, v95
	v_sub_f32_e32 v72, v72, v183
	v_sub_f32_e32 v73, v73, v183
	v_mfma_f32_32x32x16_bf16 v[0:15], v[194:197], v[190:193], v[0:15]
	ds_read2_b64 v[194:197], v181 offset0:60 offset1:62
	v_sub_f32_e32 v74, v74, v183
	v_sub_f32_e32 v75, v75, v183
	v_sub_f32_e32 v76, v76, v183
	v_sub_f32_e32 v77, v77, v183
	v_sub_f32_e32 v78, v78, v183
	v_sub_f32_e32 v79, v79, v183
	v_exp_f32_e32 v72, v72
	v_exp_f32_e32 v73, v73
	v_exp_f32_e32 v74, v74
	v_exp_f32_e32 v75, v75
	v_exp_f32_e32 v76, v76
	v_exp_f32_e32 v77, v77
	v_exp_f32_e32 v78, v78
	v_exp_f32_e32 v79, v79
	v_cvt_pk_bf16_f32 v190, v88, v89
	v_cvt_pk_bf16_f32 v191, v90, v91
	v_cvt_pk_bf16_f32 v192, v92, v93
	v_cvt_pk_bf16_f32 v193, v94, v66
	s_and_b64 vcc, exec, s[38:39]
	s_waitcnt lgkmcnt(1)
	v_mfma_f32_32x32x16_bf16 v[48:63], v[186:189], v[190:193], v[48:63]
	s_waitcnt lgkmcnt(0)
	v_mfma_f32_32x32x16_bf16 v[32:47], v[194:197], v[190:193], v[32:47]
	v_cvt_pk_bf16_f32 v190, v72, v73
	v_cvt_pk_bf16_f32 v191, v74, v75
	v_cvt_pk_bf16_f32 v192, v76, v77
	v_cvt_pk_bf16_f32 v193, v78, v79
	s_nop 1
	s_nop 1
	v_mfma_f32_32x32x16_bf16 v[16:31], v[186:189], v[190:193], v[16:31]
	v_mfma_f32_32x32x16_bf16 v[0:15], v[194:197], v[190:193], v[0:15]
	s_cbranch_vccnz .LBB0_383
	s_waitcnt vmcnt(0)
	v_add_u32_e32 v95, v172, v166
	ds_write_b128 v95, v[130:133] offset:35328
	ds_write_b128 v95, v[134:137] offset:44544
	v_add_u32_e32 v95, 0xd200, v173
	ds_write2_b64 v95, v[138:139], v[140:141] offset1:1
	v_add_u32_e32 v95, 0xd280, v173
	ds_write2_b64 v95, v[146:147], v[148:149] offset1:1
	s_branch .LBB0_383
; #define LAS __attribute__((address_space(3)))
; __device__ __forceinline__ float shx(float v, int o, int lane) { return __builtin_bit_cast(float, __builtin_amdgcn_ds_bpermute((lane ^ o) << 2, __builtin_bit_cast(int, v))); }
; template <int DK, bool IS_A>
; __device__ __forceinline__ void attn_unit(const Params& P, int l, LAS unsigned char* lds, int b, int grp, int qtok0, int nkeys) {
;     ...
;     la += shx(la, 32, lane); lb_ += shx(lb_, 32, lane);
;     { const float ia = 1.0f / la, ib = 1.0f / lb_;
; #pragma unroll
;       for (int r = 0; r < 16; ++r) { oa0[r] *= ia; oa1[r] *= ia; ob0[r] *= ib; ob1[r] *= ib; } }
;     ...
;     if (IS_A) {
;         LAS float* X = (LAS float*)lds;
;         if (s == 1) {
; #pragma unroll
;             for (int r = 0; r < 16; ++r) { X[(wq * 64 + r) * 64 + lane] = oa0[r]; X[(wq * 64 + 16 + r) * 64 + lane] = oa1[r]; X[(wq * 64 + 32 + r) * 64 + lane] = ob0[r]; X[(wq * 64 + 48 + r) * 64 + lane] = ob1[r]; }
.LBB0_400:
	v_mov_b32_e32 v242, 0x400
	ds_bpermute_b32 v64, v163, v184
	ds_bpermute_b32 v65, v163, v179
	s_waitcnt lgkmcnt(1)
	v_add_f32_e32 v64, v184, v64
	v_div_scale_f32 v66, s[10:11], v64, v64, 1.0
	v_rcp_f32_e32 v67, v66
	s_waitcnt lgkmcnt(0)
	v_add_f32_e32 v65, v179, v65
	v_fma_f32 v68, -v66, v67, 1.0
	v_fmac_f32_e32 v67, v68, v67
	v_div_scale_f32 v68, vcc, 1.0, v64, 1.0
	v_mul_f32_e32 v69, v68, v67
	v_fma_f32 v70, -v66, v69, v68
	v_fmac_f32_e32 v69, v70, v67
	v_fma_f32 v66, -v66, v69, v68
	v_div_fmas_f32 v66, v66, v67, v69
	v_div_fixup_f32 v72, v66, v64, 1.0
	v_div_scale_f32 v64, s[10:11], v65, v65, 1.0
	v_rcp_f32_e32 v66, v64
	v_pk_mul_f32 v[36:37], v[36:37], v[72:73] op_sel_hi:[1,0]
	v_pk_mul_f32 v[70:71], v[54:55], v[72:73] op_sel_hi:[1,0]
	v_pk_mul_f32 v[56:57], v[56:57], v[72:73] op_sel_hi:[1,0]
	v_fma_f32 v67, -v64, v66, 1.0
	v_fmac_f32_e32 v66, v67, v66
	v_div_scale_f32 v67, vcc, 1.0, v65, 1.0
	v_mul_f32_e32 v68, v67, v66
	v_fma_f32 v69, -v64, v68, v67
	v_fmac_f32_e32 v68, v69, v66
	v_fma_f32 v64, -v64, v68, v67
	v_div_fmas_f32 v64, v64, v66, v68
	v_div_fixup_f32 v74, v64, v65, 1.0
	v_pk_mul_f32 v[66:67], v[50:51], v[72:73] op_sel_hi:[1,0]
	v_pk_mul_f32 v[50:51], v[34:35], v[72:73] op_sel_hi:[1,0]
	v_pk_mul_f32 v[34:35], v[18:19], v[74:75] op_sel_hi:[1,0]
	v_pk_mul_f32 v[18:19], v[2:3], v[74:75] op_sel_hi:[1,0]
	v_pk_mul_f32 v[2:3], v[6:7], v[74:75] op_sel_hi:[1,0]
	v_pk_mul_f32 v[6:7], v[24:25], v[74:75] op_sel_hi:[1,0]
	v_pk_mul_f32 v[24:25], v[28:29], v[74:75] op_sel_hi:[1,0]
	v_pk_mul_f32 v[28:29], v[14:15], v[74:75] op_sel_hi:[1,0]
	v_lshlrev_b32_e32 v14, 8, v174
	v_pk_mul_f32 v[64:65], v[48:49], v[72:73] op_sel_hi:[1,0]
	v_pk_mul_f32 v[48:49], v[32:33], v[72:73] op_sel_hi:[1,0]
	v_pk_mul_f32 v[32:33], v[16:17], v[74:75] op_sel_hi:[1,0]
	v_pk_mul_f32 v[16:17], v[0:1], v[74:75] op_sel_hi:[1,0]
	v_pk_mul_f32 v[68:69], v[52:53], v[72:73] op_sel_hi:[1,0]
	v_pk_mul_f32 v[20:21], v[20:21], v[74:75] op_sel_hi:[1,0]
	v_pk_mul_f32 v[0:1], v[4:5], v[74:75] op_sel_hi:[1,0]
	v_pk_mul_f32 v[52:53], v[38:39], v[72:73] op_sel_hi:[1,0]
	v_pk_mul_f32 v[22:23], v[22:23], v[74:75] op_sel_hi:[1,0]
	v_pk_mul_f32 v[54:55], v[40:41], v[72:73] op_sel_hi:[1,0]
	v_pk_mul_f32 v[4:5], v[8:9], v[74:75] op_sel_hi:[1,0]
	v_pk_mul_f32 v[38:39], v[58:59], v[72:73] op_sel_hi:[1,0]
	v_pk_mul_f32 v[40:41], v[42:43], v[72:73] op_sel_hi:[1,0]
	v_pk_mul_f32 v[8:9], v[26:27], v[74:75] op_sel_hi:[1,0]
	v_pk_mul_f32 v[10:11], v[10:11], v[74:75] op_sel_hi:[1,0]
	v_pk_mul_f32 v[42:43], v[60:61], v[72:73] op_sel_hi:[1,0]
	v_pk_mul_f32 v[44:45], v[44:45], v[72:73] op_sel_hi:[1,0]
	v_pk_mul_f32 v[12:13], v[12:13], v[74:75] op_sel_hi:[1,0]
	v_pk_mul_f32 v[58:59], v[62:63], v[72:73] op_sel_hi:[1,0]
	v_pk_mul_f32 v[46:47], v[46:47], v[72:73] op_sel_hi:[1,0]
	v_pk_mul_f32 v[26:27], v[30:31], v[74:75] op_sel_hi:[1,0]
	v_cmp_eq_u32_e32 vcc, 1, v167
	v_add3_u32 v60, 0, v175, v14
	s_and_saveexec_b64 s[10:11], vcc
	s_cbranch_execz .LBB0_402
	ds_write2st64_b32 v60, v64, v65 offset1:1
	ds_write2st64_b32 v60, v48, v49 offset0:16 offset1:17
	ds_write2st64_b32 v60, v32, v33 offset0:32 offset1:33
	ds_write2st64_b32 v60, v16, v17 offset0:48 offset1:49
	ds_write2st64_b32 v60, v66, v67 offset0:2 offset1:3
	ds_write2st64_b32 v60, v50, v51 offset0:18 offset1:19
	ds_write2st64_b32 v60, v34, v35 offset0:34 offset1:35
	ds_write2st64_b32 v60, v18, v19 offset0:50 offset1:51
	ds_write2st64_b32 v60, v68, v69 offset0:4 offset1:5
	ds_write2st64_b32 v60, v36, v37 offset0:20 offset1:21
	ds_write2st64_b32 v60, v20, v21 offset0:36 offset1:37
	ds_write2st64_b32 v60, v0, v1 offset0:52 offset1:53
	ds_write2st64_b32 v60, v70, v71 offset0:6 offset1:7
	ds_write2st64_b32 v60, v52, v53 offset0:22 offset1:23
	ds_write2st64_b32 v60, v22, v23 offset0:38 offset1:39
	ds_write2st64_b32 v60, v2, v3 offset0:54 offset1:55
	ds_write2st64_b32 v60, v56, v57 offset0:8 offset1:9
	ds_write2st64_b32 v60, v54, v55 offset0:24 offset1:25
	ds_write2st64_b32 v60, v6, v7 offset0:40 offset1:41
	ds_write2st64_b32 v60, v4, v5 offset0:56 offset1:57
	ds_write2st64_b32 v60, v38, v39 offset0:10 offset1:11
	ds_write2st64_b32 v60, v40, v41 offset0:26 offset1:27
	ds_write2st64_b32 v60, v8, v9 offset0:42 offset1:43
	ds_write2st64_b32 v60, v10, v11 offset0:58 offset1:59
	ds_write2st64_b32 v60, v42, v43 offset0:12 offset1:13
	ds_write2st64_b32 v60, v44, v45 offset0:28 offset1:29
	ds_write2st64_b32 v60, v24, v25 offset0:44 offset1:45
	ds_write2st64_b32 v60, v12, v13 offset0:60 offset1:61
	ds_write2st64_b32 v60, v58, v59 offset0:14 offset1:15
	ds_write2st64_b32 v60, v46, v47 offset0:30 offset1:31
	ds_write2st64_b32 v60, v26, v27 offset0:46 offset1:47
	ds_write2st64_b32 v60, v28, v29 offset0:62 offset1:63
